# R5 QK->SV seam: dropped the agent-scope buffer_inv (P is produced and consumed by the same workgroup; vmcnt(0)+barrier is the workgroup-scope handoff)
# speedup vs baseline: 1.0212x; 1.0052x over previous
; template <class Epi, class Sched>
; __device__ __forceinline__ void gemm_phase(LAS unsigned char* lds, const Sched& S, const Epi& E) {
;     ...
;     int sR, sRb, sC2;
;     { int R, C; stage_rc(tid * 16, R, C); sR = R; sRb = (R & ~31) + perm32(R & 31); sC2 = C * 2; }
;     const size_t kstep = (size_t)(BK * 2);
;     const unsigned ldsbase = (unsigned)(size_t)lds + (unsigned)wid * 1024u;
;     const int aoff = lds_byte(wr * 64 + fr, fq * 8), boff = lds_byte(wc * 32 + fr, fq * 8);
;     ...
;     int ui = 0;
;     const char* cA; const char* cB; unsigned hA, hB; int nt; unsigned voffA, voffB;
;     { Unit u0; if (!S.next(0, u0)) return;
;       cA = u0.A; cB = u0.B; hA = (unsigned)HALF * u0.lda2; hB = (unsigned)HALF * u0.ldb2; nt = u0.nt;
;       voffA = (unsigned)(sR * u0.lda2 + sC2); voffB = (unsigned)(sRb * u0.ldb2 + sC2); }
;     f32x4 acc[2][2][4][2];
; #pragma unroll
;     for (int a = 0; a < 2; ++a)
; #pragma unroll
;         for (int b = 0; b < 2; ++b)
; #pragma unroll
;             for (int m = 0; m < 4; ++m)
; #pragma unroll
;                 for (int n = 0; n < 2; ++n) acc[a][b][m][n] = (f32x4){0.f, 0.f, 0.f, 0.f};
;     bf16x8 At[4][2], B0[2][2], B1[2][2];
;     PG8_STAGE(PG8_SB(0, 0), cB, voffB, hB / 2); PG8_STAGE(PG8_SB(0, 1), cB + hB, voffB, hB / 2); PG8_STAGE(PG8_SA(0, 0), cA, voffA, hA / 2); PG8_STAGE(PG8_SA(0, 1), cA + hA, voffA, hA / 2);
; __global__ void __launch_bounds__(512, 2) fwd_megakernel(Params Parg) {
;     ...
;             __builtin_amdgcn_fence(__ATOMIC_ACQUIRE, "agent");
;             { PHASE_BEGIN
;               bf16_t* pscr = (bf16_t*)(ws + WS_PSCR + (size_t)(bid >> 1) * (256 * D * 2) + (size_t)(bid & 1) * (CH * 2));
;               const int ib = item & 1, h = (item >> 1) & 3, n = item >> 3;
;               SVSched S{(const char*)(ws + WS_KTQK) + ((size_t)(n * CH + ib * 256) * D + h * 256) * 2, (const char*)(ws + WS_SB) + ((size_t)((h * NCH + n) * 512) * 512) * 2,
;                         (const char*)(ws + WS_VT) + ((size_t)((h * NCH + n) * 512) * 512) * 2, (const char*)pscr, item};
;               EpiSV E; E.o = (bf16_t*)pp->out + (size_t)b * L * 2048; E.dec = WSP(float, WS_DEC); gemm_phase(lds, S, E); }
.LBB0_836:
	v_readlane_b32 s0, v254, 62
	v_readlane_b32 s1, v254, 63
	s_mov_b64 s[4:5], s[0:1]
	s_waitcnt vmcnt(0)
	s_barrier
	s_waitcnt vmcnt(0)
	s_load_dwordx4 s[8:11], s[4:5], 0xc8
	s_ashr_i32 s6, s73, 3
	s_lshl_b32 s7, s6, 9
	s_or_b32 s4, s7, s51
	s_ashr_i32 s5, s4, 31
	s_lshl_b32 s12, s72, 9
	s_lshl_b64 s[4:5], s[4:5], 11
	v_mov_b32_e32 v0, v176
	s_waitcnt lgkmcnt(0)
	s_add_u32 s4, s10, s4
	s_addc_u32 s5, s11, s5
	s_add_u32 s34, s4, s12
	v_mov_b32_e32 v0, v176
	s_addc_u32 s35, s5, 0
	s_add_u32 s26, s34, 0x8900000
	v_bfe_i32 v3, v0, 27, 1
	v_lshlrev_b32_e32 v1, 4, v0
	v_lshrrev_b32_e32 v3, 22, v3
	s_addc_u32 s27, s35, 0
	s_lshl_b32 s4, s72, 14
	v_add_u32_e32 v3, v1, v3
	s_add_i32 s4, s4, s7
	v_and_b32_e32 v3, 0xfffffc00, v3
	s_ashr_i32 s5, s4, 31
	v_sub_u32_e32 v1, v1, v3
	s_lshl_b64 s[16:17], s[4:5], 10
	v_ashrrev_i32_e32 v2, 31, v0
	v_lshrrev_b32_e32 v3, 4, v1
	s_add_u32 s7, s10, s16
	v_lshrrev_b32_e32 v2, 26, v2
	v_bitop3_b32 v1, v3, v1, 32 bitop3:0x6c
	s_addc_u32 s24, s11, s17
	v_add_u32_e32 v2, v0, v2
	v_ashrrev_i32_e32 v4, 31, v1
	s_add_u32 s38, s7, 0x10900000
	v_readfirstlane_b32 s22, v0
	v_ashrrev_i32_e32 v2, 6, v2
	v_lshrrev_b32_e32 v4, 26, v4
	s_addc_u32 s39, s24, 0
	s_ashr_i32 s48, s22, 6
	v_lshlrev_b32_e32 v3, 3, v2
	v_add_u32_e32 v4, v1, v4
	v_and_b32_e32 v3, -16, v3
	v_ashrrev_i32_e32 v5, 6, v4
	v_and_b32_e32 v4, 0xc0, v4
	s_lshl_b32 s4, s48, 10
	v_add_u32_e32 v3, v5, v3
	v_sub_u32_e32 v1, v1, v4
	v_and_b32_e32 v5, 3, v5
	s_mov_b32 s5, 0x3fffe0
	s_add_i32 s4, s4, 0
	s_ashr_i32 s23, s22, 8
	v_lshlrev_b32_e32 v2, 5, v2
	v_ashrrev_i16_sdwa v1, v157, sext(v1) dst_sel:DWORD dst_unused:UNUSED_PAD src0_sel:DWORD src1_sel:BYTE_0
	v_lshlrev_b32_e32 v4, 1, v3
	v_lshrrev_b32_e32 v6, 2, v3
	v_and_or_b32 v5, v3, s5, v5
	s_add_i32 s5, s4, 0x10000
	v_bfe_i32 v1, v1, 0, 16
	v_and_b32_e32 v4, 24, v4
	v_and_b32_e32 v6, 4, v6
	v_and_b32_e32 v2, 32, v2
	s_add_u32 s14, s7, 0x10910000
	v_or3_b32 v4, v5, v6, v4
	v_add_lshl_u32 v1, v2, v1, 1
	s_addc_u32 s15, s24, 0
	s_add_i32 s12, s4, 0x12000
	v_lshl_add_u32 v128, v4, 10, v1
	s_mov_b32 m0, s5
	s_nop 0
	global_load_lds_dwordx4 v128, s[38:39]
	s_mov_b32 m0, s12
	s_add_u32 s30, s7, 0x10920000
	global_load_lds_dwordx4 v128, s[14:15]
	s_addc_u32 s31, s24, 0
	s_add_i32 s14, s4, 0x14000
	s_mov_b32 m0, s14
	s_nop 0
	global_load_lds_dwordx4 v128, s[30:31]
	s_add_u32 s30, s7, 0x10930000
	s_addc_u32 s31, s24, 0
	s_add_i32 s15, s4, 0x16000
	s_mov_b32 m0, s15
	s_nop 0
	global_load_lds_dwordx4 v128, s[30:31]
	s_add_u32 s30, s34, 0x8920000
	v_lshl_add_u32 v172, v3, 11, v1
	s_mov_b32 m0, s4
	s_nop 0
	global_load_lds_dwordx4 v172, s[26:27]
	s_addc_u32 s31, s35, 0
	s_add_i32 s24, s4, 0x2000
	s_mov_b32 m0, s24
	s_nop 0
	global_load_lds_dwordx4 v172, s[30:31]
	s_add_u32 s30, s34, 0x8940000
	s_addc_u32 s31, s35, 0
	s_add_i32 s33, s4, 0x4000
	s_mov_b32 m0, s33
	s_nop 0
	global_load_lds_dwordx4 v172, s[30:31]
	s_add_u32 s30, s34, 0x8960000
	s_addc_u32 s31, s35, 0
	s_add_i32 s34, s4, 0x6000
	s_mov_b32 m0, s34
	s_nop 0
	global_load_lds_dwordx4 v172, s[30:31]
	s_cmp_eq_u32 s23, 1
	s_cselect_b64 s[40:41], -1, 0
	s_cmp_lg_u32 s23, 1
	s_cbranch_scc1 .LBB0_838
	s_barrier
